# grid barrier: the 16th arriver of each XCD issues an early non-blocking L2 write-back so the leader's flush has less left
# baseline (speedup 1.0000x reference)
.LBB0_571:
	s_or_b64 exec, exec, s[2:3]
	v_cvt_f32_u32_e32 v5, v3
	s_waitcnt vmcnt(0)
	v_readfirstlane_b32 s2, v4
	v_sub_u32_e32 v4, 0, v3
	v_rcp_iflag_f32_e32 v5, v5
	v_add_u32_e32 v6, s2, v0
	v_mul_f32_e32 v5, 0x4f7ffffe, v5
	v_cvt_u32_f32_e32 v5, v5
	v_mul_lo_u32 v0, v4, v5
	v_mul_hi_u32 v0, v5, v0
	v_add_u32_e32 v0, v5, v0
	v_mul_hi_u32 v0, v6, v0
	v_mul_lo_u32 v4, v0, v3
	v_sub_u32_e32 v4, v6, v4
	v_add_u32_e32 v5, 1, v0
	v_cmp_ge_u32_e32 vcc, v4, v3
	s_nop 1
	v_cndmask_b32_e32 v0, v0, v5, vcc
	v_sub_u32_e32 v5, v4, v3
	v_cndmask_b32_e32 v4, v4, v5, vcc
	v_add_u32_e32 v5, 1, v0
	v_cmp_ge_u32_e32 vcc, v4, v3
	v_add_u32_e32 v4, 1, v6
	s_nop 0
	v_cndmask_b32_e32 v0, v0, v5, vcc
	v_mul_lo_u32 v5, v3, v0
	v_add_u32_e32 v3, v5, v3
	v_cmp_ne_u32_e32 vcc, v4, v3
	s_and_saveexec_b64 s[2:3], vcc
	s_xor_b64 s[2:3], exec, s[2:3]
	s_cbranch_execz .LBB0_585
	v_readlane_b32 s4, v215, 22
	v_readlane_b32 s5, v215, 23
	s_waitcnt lgkmcnt(0)
	s_nop 3
	v_sub_u32_e32 v5, v3, v4
	v_cmp_eq_u32_e32 vcc, 16, v5
	s_cbranch_vccz .Lbar_noearly
	buffer_wbl2 sc1
.Lbar_noearly:
	buffer_inv sc1
	global_load_dword v2, v1, s[4:5] sc1
	s_waitcnt vmcnt(0)
	v_cmp_eq_u32_e32 vcc, v2, v0
	s_and_saveexec_b64 s[4:5], vcc
	s_cbranch_execz .LBB0_584
	s_mov_b32 s16, 1
	s_mov_b64 s[6:7], 0
	s_branch .LBB0_575
